# nt (non-temporal) on the 8 attention-epilogue output stores, on top of v42
# baseline (speedup 1.0000x reference)
.LBB0_446:
	s_andn2_b64 vcc, exec, s[4:5]
	s_waitcnt lgkmcnt(0)
	s_barrier
	s_cbranch_vccnz .LBB0_427
	ds_read2st64_b32 v[26:27], v24 offset1:1
	ds_read2st64_b32 v[28:29], v24 offset0:2 offset1:3
	ds_read2st64_b32 v[30:31], v24 offset0:4 offset1:5
	ds_read2st64_b32 v[46:47], v24 offset0:6 offset1:7
	ds_read2st64_b32 v[62:63], v24 offset0:8 offset1:9
	ds_read2st64_b32 v[96:97], v24 offset0:10 offset1:11
	ds_read2st64_b32 v[98:99], v24 offset0:12 offset1:13
	ds_read2st64_b32 v[100:101], v24 offset0:14 offset1:15
	ds_read2st64_b32 v[102:103], v24 offset0:16 offset1:17
	ds_read2st64_b32 v[104:105], v24 offset0:18 offset1:19
	ds_read2st64_b32 v[106:107], v24 offset0:20 offset1:21
	ds_read2st64_b32 v[108:109], v24 offset0:22 offset1:23
	ds_read2st64_b32 v[110:111], v24 offset0:24 offset1:25
	ds_read2st64_b32 v[114:115], v24 offset0:26 offset1:27
	ds_read2st64_b32 v[116:117], v24 offset0:28 offset1:29
	ds_read2st64_b32 v[118:119], v24 offset0:30 offset1:31
	ds_read2st64_b32 v[120:121], v24 offset0:32 offset1:33
	ds_read2st64_b32 v[122:123], v24 offset0:34 offset1:35
	ds_read2st64_b32 v[124:125], v24 offset0:36 offset1:37
	ds_read2st64_b32 v[126:127], v24 offset0:38 offset1:39
	ds_read2st64_b32 v[132:133], v24 offset0:40 offset1:41
	ds_read2st64_b32 v[134:135], v24 offset0:42 offset1:43
	ds_read2st64_b32 v[136:137], v24 offset0:44 offset1:45
	ds_read2st64_b32 v[138:139], v24 offset0:46 offset1:47
	ds_read2st64_b32 v[140:141], v24 offset0:56 offset1:57
	ds_read2st64_b32 v[142:143], v24 offset0:58 offset1:59
	ds_read2st64_b32 v[92:93], v24 offset0:60 offset1:61
	ds_read2st64_b32 v[94:95], v24 offset0:62 offset1:63
	ds_read2st64_b32 v[144:145], v24 offset0:48 offset1:49
	ds_read2st64_b32 v[146:147], v24 offset0:50 offset1:51
	ds_read2st64_b32 v[150:151], v24 offset0:52 offset1:53
	ds_read2st64_b32 v[24:25], v24 offset0:54 offset1:55
	s_waitcnt lgkmcnt(14)
	v_pk_add_f32 v[88:89], v[88:89], v[26:27] neg_lo:[0,1] neg_hi:[0,1]
	v_lshlrev_b32_e32 v175, 2, v179
	v_pk_add_f32 v[90:91], v[90:91], v[28:29] neg_lo:[0,1] neg_hi:[0,1]
	v_pk_mul_f32 v[158:159], v[88:89], v[88:89]
	s_waitcnt lgkmcnt(5)
	v_pk_add_f32 v[16:17], v[16:17], v[92:93] neg_lo:[0,1] neg_hi:[0,1]
	s_waitcnt lgkmcnt(4)
	v_pk_add_f32 v[18:19], v[18:19], v[94:95] neg_lo:[0,1] neg_hi:[0,1]
	global_load_dwordx4 v[92:95], v175, s[70:71]
	global_load_dwordx4 v[198:201], v175, s[70:71] offset:32
	global_load_dwordx4 v[202:205], v175, s[70:71] offset:64
	global_load_dwordx4 v[206:209], v175, s[70:71] offset:96
	global_load_dwordx4 v[210:213], v175, s[70:71] offset:128
	global_load_dwordx4 v[214:217], v175, s[70:71] offset:160
	global_load_dwordx4 v[218:221], v175, s[70:71] offset:192
	global_load_dwordx4 v[222:225], v175, s[70:71] offset:224
	global_load_dwordx4 v[226:229], v175, s[70:71] offset:256
	global_load_dwordx4 v[230:233], v175, s[70:71] offset:288
	global_load_dwordx4 v[234:237], v175, s[70:71] offset:320
	global_load_dwordx4 v[238:241], v175, s[70:71] offset:352
	global_load_dwordx4 v[242:245], v175, s[70:71] offset:384
	global_load_dwordx4 v[246:249], v175, s[70:71] offset:416
	global_load_dwordx4 v[184:187], v175, s[70:71] offset:448
	global_load_dwordx4 v[128:131], v175, s[70:71] offset:480
	v_pk_mul_f32 v[156:157], v[90:91], v[90:91]
	v_pk_add_f32 v[22:23], v[22:23], v[142:143] neg_lo:[0,1] neg_hi:[0,1]
	v_add_f32_e32 v142, v158, v159
	v_pk_add_f32 v[82:83], v[82:83], v[30:31] neg_lo:[0,1] neg_hi:[0,1]
	v_add_f32_e32 v142, v142, v156
	v_pk_mul_f32 v[162:163], v[82:83], v[82:83]
	v_add_f32_e32 v142, v142, v157
	v_pk_add_f32 v[86:87], v[86:87], v[46:47] neg_lo:[0,1] neg_hi:[0,1]
	v_add_f32_e32 v142, v142, v162
	v_pk_mul_f32 v[160:161], v[86:87], v[86:87]
	v_add_f32_e32 v142, v142, v163
	v_pk_add_f32 v[62:63], v[80:81], v[62:63] neg_lo:[0,1] neg_hi:[0,1]
	v_add_f32_e32 v142, v142, v160
	v_pk_mul_f32 v[80:81], v[62:63], v[62:63]
	v_add_f32_e32 v142, v142, v161
	v_pk_add_f32 v[84:85], v[84:85], v[96:97] neg_lo:[0,1] neg_hi:[0,1]
	v_add_f32_e32 v80, v142, v80
	v_pk_mul_f32 v[96:97], v[84:85], v[84:85]
	v_add_f32_e32 v80, v80, v81
	v_pk_add_f32 v[72:73], v[72:73], v[98:99] neg_lo:[0,1] neg_hi:[0,1]
	v_add_f32_e32 v80, v80, v96
	v_pk_mul_f32 v[98:99], v[72:73], v[72:73]
	v_add_f32_e32 v80, v80, v97
	v_pk_add_f32 v[78:79], v[78:79], v[100:101] neg_lo:[0,1] neg_hi:[0,1]
	v_add_f32_e32 v80, v80, v98
	v_pk_mul_f32 v[100:101], v[78:79], v[78:79]
	v_add_f32_e32 v80, v80, v99
	v_pk_add_f32 v[68:69], v[68:69], v[102:103] neg_lo:[0,1] neg_hi:[0,1]
	v_add_f32_e32 v80, v80, v100
	v_pk_mul_f32 v[102:103], v[68:69], v[68:69]
	v_add_f32_e32 v80, v80, v101
	v_pk_add_f32 v[76:77], v[76:77], v[104:105] neg_lo:[0,1] neg_hi:[0,1]
	v_add_f32_e32 v80, v80, v102
	v_pk_mul_f32 v[104:105], v[76:77], v[76:77]
	v_add_f32_e32 v80, v80, v103
	v_pk_add_f32 v[66:67], v[66:67], v[106:107] neg_lo:[0,1] neg_hi:[0,1]
	v_add_f32_e32 v80, v80, v104
	v_pk_mul_f32 v[106:107], v[66:67], v[66:67]
	v_add_f32_e32 v80, v80, v105
	v_pk_add_f32 v[74:75], v[74:75], v[108:109] neg_lo:[0,1] neg_hi:[0,1]
	v_add_f32_e32 v80, v80, v106
	v_pk_mul_f32 v[108:109], v[74:75], v[74:75]
	v_add_f32_e32 v80, v80, v107
	v_pk_add_f32 v[64:65], v[64:65], v[110:111] neg_lo:[0,1] neg_hi:[0,1]
	v_add_f32_e32 v80, v80, v108
	v_pk_mul_f32 v[110:111], v[64:65], v[64:65]
	v_add_f32_e32 v80, v80, v109
	v_pk_add_f32 v[70:71], v[70:71], v[114:115] neg_lo:[0,1] neg_hi:[0,1]
	v_add_f32_e32 v80, v80, v110
	v_pk_mul_f32 v[114:115], v[70:71], v[70:71]
	v_add_f32_e32 v80, v80, v111
	v_pk_add_f32 v[54:55], v[54:55], v[116:117] neg_lo:[0,1] neg_hi:[0,1]
	v_add_f32_e32 v80, v80, v114
	v_pk_mul_f32 v[116:117], v[54:55], v[54:55]
	v_add_f32_e32 v80, v80, v115
	v_pk_add_f32 v[60:61], v[60:61], v[118:119] neg_lo:[0,1] neg_hi:[0,1]
	v_add_f32_e32 v80, v80, v116
	v_pk_mul_f32 v[118:119], v[60:61], v[60:61]
	v_add_f32_e32 v80, v80, v117
	v_pk_add_f32 v[50:51], v[50:51], v[120:121] neg_lo:[0,1] neg_hi:[0,1]
	v_add_f32_e32 v80, v80, v118
	v_pk_mul_f32 v[120:121], v[50:51], v[50:51]
	v_add_f32_e32 v80, v80, v119
	v_pk_add_f32 v[58:59], v[58:59], v[122:123] neg_lo:[0,1] neg_hi:[0,1]
	v_add_f32_e32 v80, v80, v120
	v_pk_mul_f32 v[122:123], v[58:59], v[58:59]
	v_add_f32_e32 v80, v80, v121
	v_pk_add_f32 v[48:49], v[48:49], v[124:125] neg_lo:[0,1] neg_hi:[0,1]
	v_add_f32_e32 v80, v80, v122
	v_pk_mul_f32 v[124:125], v[48:49], v[48:49]
	v_add_f32_e32 v80, v80, v123
	v_pk_add_f32 v[56:57], v[56:57], v[126:127] neg_lo:[0,1] neg_hi:[0,1]
	v_add_f32_e32 v80, v80, v124
	v_pk_mul_f32 v[126:127], v[56:57], v[56:57]
	v_add_f32_e32 v80, v80, v125
	v_pk_add_f32 v[132:133], v[40:41], v[132:133] neg_lo:[0,1] neg_hi:[0,1]
	v_add_f32_e32 v80, v80, v126
	v_pk_mul_f32 v[40:41], v[132:133], v[132:133]
	v_add_f32_e32 v80, v80, v127
	v_pk_add_f32 v[46:47], v[52:53], v[134:135] neg_lo:[0,1] neg_hi:[0,1]
	v_add_f32_e32 v40, v80, v40
	v_pk_mul_f32 v[52:53], v[46:47], v[46:47]
	v_add_f32_e32 v40, v40, v41
	v_pk_add_f32 v[36:37], v[36:37], v[136:137] neg_lo:[0,1] neg_hi:[0,1]
	v_add_f32_e32 v40, v40, v52
	v_pk_mul_f32 v[134:135], v[36:37], v[36:37]
	v_add_f32_e32 v40, v40, v53
	v_pk_add_f32 v[30:31], v[44:45], v[138:139] neg_lo:[0,1] neg_hi:[0,1]
	v_add_f32_e32 v40, v40, v134
	v_pk_mul_f32 v[44:45], v[30:31], v[30:31]
	v_add_f32_e32 v40, v40, v135
	s_waitcnt lgkmcnt(3)
	v_pk_add_f32 v[34:35], v[34:35], v[144:145] neg_lo:[0,1] neg_hi:[0,1]
	v_add_f32_e32 v40, v40, v44
	v_pk_mul_f32 v[136:137], v[34:35], v[34:35]
	v_add_f32_e32 v40, v40, v45
	s_waitcnt lgkmcnt(2)
	v_pk_add_f32 v[26:27], v[42:43], v[146:147] neg_lo:[0,1] neg_hi:[0,1]
	v_add_f32_e32 v40, v40, v136
	v_pk_mul_f32 v[42:43], v[26:27], v[26:27]
	v_add_f32_e32 v40, v40, v137
	s_waitcnt lgkmcnt(1)
	v_pk_add_f32 v[28:29], v[32:33], v[150:151] neg_lo:[0,1] neg_hi:[0,1]
	v_add_f32_e32 v40, v40, v42
	v_pk_mul_f32 v[32:33], v[28:29], v[28:29]
	v_add_f32_e32 v40, v40, v43
	s_waitcnt lgkmcnt(0)
	v_pk_add_f32 v[24:25], v[38:39], v[24:25] neg_lo:[0,1] neg_hi:[0,1]
	v_add_f32_e32 v32, v40, v32
	v_pk_mul_f32 v[38:39], v[24:25], v[24:25]
	v_add_f32_e32 v32, v32, v33
	v_pk_add_f32 v[20:21], v[20:21], v[140:141] neg_lo:[0,1] neg_hi:[0,1]
	v_add_f32_e32 v32, v32, v38
	v_pk_mul_f32 v[140:141], v[20:21], v[20:21]
	v_add_f32_e32 v32, v32, v39
	v_add_f32_e32 v32, v32, v140
	v_pk_mul_f32 v[138:139], v[22:23], v[22:23]
	v_add_f32_e32 v32, v32, v141
	v_add_f32_e32 v32, v32, v138
	v_pk_mul_f32 v[152:153], v[16:17], v[16:17]
	v_add_f32_e32 v32, v32, v139
	v_add_f32_e32 v32, v32, v152
	v_pk_mul_f32 v[154:155], v[18:19], v[18:19]
	v_add_f32_e32 v32, v32, v153
	v_add_f32_e32 v32, v32, v154
	v_add_f32_e32 v38, v32, v155
	ds_bpermute_b32 v39, v195, v38
	v_lshlrev_b64 v[32:33], 11, v[176:177]
	v_lshl_add_u64 v[32:33], s[74:75], 0, v[32:33]
	v_lshl_add_u64 v[32:33], v[32:33], 0, s[12:13]
	v_lshlrev_b32_e32 v166, 1, v179
	s_waitcnt lgkmcnt(0)
	v_add_f32_e32 v38, v38, v39
	v_fmamk_f32 v38, v38, 0x3c000000, v193
	v_mul_f32_e32 v39, 0x4b800000, v38
	v_cmp_gt_f32_e32 vcc, s27, v38
	v_lshl_add_u64 v[32:33], v[32:33], 0, v[166:167]
	v_lshl_add_u64 v[44:45], v[32:33], 0, s[14:15]
	v_cndmask_b32_e32 v38, v38, v39, vcc
	v_rsq_f32_e32 v38, v38
	s_nop 0
	v_mul_f32_e32 v39, 0x45800000, v38
	v_cndmask_b32_e32 v38, v38, v39, vcc
	v_mul_f32_e32 v42, 0x3f4ccccd, v38
	v_pk_mul_f32 v[38:39], v[88:89], v[42:43] op_sel_hi:[1,0]
	v_pk_mul_f32 v[40:41], v[90:91], v[42:43] op_sel_hi:[1,0]
	s_waitcnt vmcnt(0)
	v_pk_mul_f32 v[38:39], v[92:93], v[38:39]
	v_pk_mul_f32 v[40:41], v[94:95], v[40:41]
	v_cvt_pk_bf16_f32 v92, v38, v39
	v_cvt_pk_bf16_f32 v93, v40, v41
	v_and_b32_e32 v112, 32, v190
	v_lshrrev_b32_e32 v112, 2, v112
	v_mov_b32_e32 v113, 0
	v_pk_mul_f32 v[52:53], v[84:85], v[42:43] op_sel_hi:[1,0]
	s_nop 0
	v_lshl_add_u64 v[40:41], v[44:45], 0, v[112:113]
	v_pk_mul_f32 v[32:33], v[82:83], v[42:43] op_sel_hi:[1,0]
	v_pk_mul_f32 v[46:47], v[46:47], v[42:43] op_sel_hi:[1,0]
	v_pk_mul_f32 v[30:31], v[30:31], v[42:43] op_sel_hi:[1,0]
	v_pk_mul_f32 v[34:35], v[34:35], v[42:43] op_sel_hi:[1,0]
	v_pk_mul_f32 v[26:27], v[26:27], v[42:43] op_sel_hi:[1,0]
	v_pk_mul_f32 v[24:25], v[24:25], v[42:43] op_sel_hi:[1,0]
	v_pk_mul_f32 v[20:21], v[20:21], v[42:43] op_sel_hi:[1,0]
	v_pk_mul_f32 v[22:23], v[22:23], v[42:43] op_sel_hi:[1,0]
	v_pk_mul_f32 v[16:17], v[16:17], v[42:43] op_sel_hi:[1,0]
	v_pk_mul_f32 v[18:19], v[18:19], v[42:43] op_sel_hi:[1,0]
	v_pk_mul_f32 v[32:33], v[198:199], v[32:33]
	v_pk_mul_f32 v[38:39], v[86:87], v[42:43] op_sel_hi:[1,0]
	v_cvt_pk_bf16_f32 v94, v32, v33
	v_pk_mul_f32 v[38:39], v[200:201], v[38:39]
	s_nop 0
	v_cvt_pk_bf16_f32 v95, v38, v39
	s_nop 1
	v_permlane32_swap_b32_e32 v92, v94
	v_permlane32_swap_b32_e32 v93, v95
	global_store_dwordx4 v[40:41], v[92:95], off nt
	v_pk_mul_f32 v[32:33], v[62:63], v[42:43] op_sel_hi:[1,0]
	v_pk_mul_f32 v[32:33], v[202:203], v[32:33]
	v_pk_mul_f32 v[38:39], v[204:205], v[52:53]
	v_cvt_pk_bf16_f32 v202, v32, v33
	v_cvt_pk_bf16_f32 v203, v38, v39
	v_pk_mul_f32 v[32:33], v[72:73], v[42:43] op_sel_hi:[1,0]
	v_pk_mul_f32 v[52:53], v[78:79], v[42:43] op_sel_hi:[1,0]
	v_pk_mul_f32 v[32:33], v[206:207], v[32:33]
	v_pk_mul_f32 v[38:39], v[208:209], v[52:53]
	v_cvt_pk_bf16_f32 v204, v32, v33
	v_cvt_pk_bf16_f32 v205, v38, v39
	s_nop 1
	v_permlane32_swap_b32_e32 v202, v204
	v_permlane32_swap_b32_e32 v203, v205
	global_store_dwordx4 v[40:41], v[202:205], off offset:32 nt
	v_pk_mul_f32 v[32:33], v[68:69], v[42:43] op_sel_hi:[1,0]
	v_pk_mul_f32 v[52:53], v[76:77], v[42:43] op_sel_hi:[1,0]
	v_pk_mul_f32 v[32:33], v[210:211], v[32:33]
	v_pk_mul_f32 v[38:39], v[212:213], v[52:53]
	v_cvt_pk_bf16_f32 v210, v32, v33
	v_cvt_pk_bf16_f32 v211, v38, v39
	v_pk_mul_f32 v[32:33], v[66:67], v[42:43] op_sel_hi:[1,0]
	v_pk_mul_f32 v[52:53], v[74:75], v[42:43] op_sel_hi:[1,0]
	v_pk_mul_f32 v[32:33], v[214:215], v[32:33]
	v_pk_mul_f32 v[38:39], v[216:217], v[52:53]
	v_cvt_pk_bf16_f32 v212, v32, v33
	v_cvt_pk_bf16_f32 v213, v38, v39
	s_nop 1
	v_permlane32_swap_b32_e32 v210, v212
	v_permlane32_swap_b32_e32 v211, v213
	global_store_dwordx4 v[40:41], v[210:213], off offset:64 nt
	v_pk_mul_f32 v[32:33], v[64:65], v[42:43] op_sel_hi:[1,0]
	v_pk_mul_f32 v[52:53], v[70:71], v[42:43] op_sel_hi:[1,0]
	v_pk_mul_f32 v[32:33], v[32:33], v[218:219]
	v_pk_mul_f32 v[38:39], v[52:53], v[220:221]
	v_cvt_pk_bf16_f32 v218, v32, v33
	v_cvt_pk_bf16_f32 v219, v38, v39
	v_pk_mul_f32 v[32:33], v[54:55], v[42:43] op_sel_hi:[1,0]
	v_pk_mul_f32 v[52:53], v[60:61], v[42:43] op_sel_hi:[1,0]
	v_pk_mul_f32 v[32:33], v[32:33], v[222:223]
	v_pk_mul_f32 v[38:39], v[52:53], v[224:225]
	v_cvt_pk_bf16_f32 v220, v32, v33
	v_cvt_pk_bf16_f32 v221, v38, v39
	s_nop 1
	v_permlane32_swap_b32_e32 v218, v220
	v_permlane32_swap_b32_e32 v219, v221
	global_store_dwordx4 v[40:41], v[218:221], off offset:96 nt
	v_pk_mul_f32 v[32:33], v[50:51], v[42:43] op_sel_hi:[1,0]
	v_pk_mul_f32 v[50:51], v[58:59], v[42:43] op_sel_hi:[1,0]
	v_pk_mul_f32 v[32:33], v[32:33], v[226:227]
	v_pk_mul_f32 v[38:39], v[50:51], v[228:229]
	v_cvt_pk_bf16_f32 v226, v32, v33
	v_cvt_pk_bf16_f32 v227, v38, v39
	v_pk_mul_f32 v[32:33], v[48:49], v[42:43] op_sel_hi:[1,0]
	v_pk_mul_f32 v[48:49], v[56:57], v[42:43] op_sel_hi:[1,0]
	v_pk_mul_f32 v[32:33], v[32:33], v[230:231]
	v_pk_mul_f32 v[38:39], v[48:49], v[232:233]
	v_cvt_pk_bf16_f32 v228, v32, v33
	v_cvt_pk_bf16_f32 v229, v38, v39
	s_nop 1
	v_permlane32_swap_b32_e32 v226, v228
	v_permlane32_swap_b32_e32 v227, v229
	global_store_dwordx4 v[40:41], v[226:229], off offset:128 nt
	v_pk_mul_f32 v[32:33], v[132:133], v[42:43] op_sel_hi:[1,0]
	v_pk_mul_f32 v[32:33], v[32:33], v[234:235]
	v_pk_mul_f32 v[38:39], v[46:47], v[236:237]
	v_cvt_pk_bf16_f32 v234, v32, v33
	v_cvt_pk_bf16_f32 v235, v38, v39
	v_pk_mul_f32 v[32:33], v[36:37], v[42:43] op_sel_hi:[1,0]
	v_pk_mul_f32 v[30:31], v[30:31], v[240:241]
	v_pk_mul_f32 v[32:33], v[32:33], v[238:239]
	s_nop 0
	v_cvt_pk_bf16_f32 v236, v32, v33
	v_cvt_pk_bf16_f32 v237, v30, v31
	s_nop 1
	v_permlane32_swap_b32_e32 v234, v236
	v_permlane32_swap_b32_e32 v235, v237
	global_store_dwordx4 v[40:41], v[234:237], off offset:160 nt
	v_pk_mul_f32 v[30:31], v[34:35], v[242:243]
	v_pk_mul_f32 v[26:27], v[26:27], v[244:245]
	v_cvt_pk_bf16_f32 v242, v30, v31
	v_cvt_pk_bf16_f32 v243, v26, v27
	v_pk_mul_f32 v[26:27], v[28:29], v[42:43] op_sel_hi:[1,0]
	v_pk_mul_f32 v[24:25], v[24:25], v[248:249]
	v_pk_mul_f32 v[26:27], v[26:27], v[246:247]
	s_nop 0
	v_cvt_pk_bf16_f32 v244, v26, v27
	v_cvt_pk_bf16_f32 v245, v24, v25
	s_nop 1
	v_permlane32_swap_b32_e32 v242, v244
	v_permlane32_swap_b32_e32 v243, v245
	global_store_dwordx4 v[40:41], v[242:245], off offset:192 nt
	v_pk_mul_f32 v[20:21], v[20:21], v[184:185]
	v_pk_mul_f32 v[22:23], v[22:23], v[186:187]
	v_cvt_pk_bf16_f32 v184, v20, v21
	v_cvt_pk_bf16_f32 v185, v22, v23
	v_pk_mul_f32 v[16:17], v[16:17], v[128:129]
	v_pk_mul_f32 v[18:19], v[18:19], v[130:131]
	v_cvt_pk_bf16_f32 v186, v16, v17
	v_cvt_pk_bf16_f32 v187, v18, v19
	s_nop 1
	v_permlane32_swap_b32_e32 v184, v186
	v_permlane32_swap_b32_e32 v185, v187
	global_store_dwordx4 v[40:41], v[184:187], off offset:224 nt
	s_branch .LBB0_427
